# panel-counter poll loops sleep 6 instead of 2 between polls (otherwise v093)
# speedup vs baseline: 1.0031x; 1.0031x over previous
; #define lane lane_id()
; __global__ void __launch_bounds__(NWAVES * 64, 2) fwd_kernel(Args a) {
;     ...
;     if (IN(1)) for (int rep = 0; rep < NREP(1); ++rep) {
;         pg8::Gemm g{HN0, WT1, NTOK, 3 * GW, DM}; pg8::ConvOrder S; S.init(NTOK, 3 * GW, G, bx);
;         S.w2 = a_w_out; S.w3 = b_w_in; S.w4 = b_w_out; S.g1 = norm_g + DM; S.t2 = WT2; S.t3 = WT3; S.t4 = WT4; S.gw = gw; S.ngw = NGW; S.trigger = (G == 256) ? CONV_TRIGGER : 0; S.ln = lane; S.sw = lds + 131072 + wave * 2048; S.n_done = 0;
;         pg8::EpiGmlpIn E{U, V, VSS};
;         pg8::gemm_phase<pg8::EpiGmlpIn, pg8::ConvOrder, GEMM_ALIGN, GEMM_SP2>(lds, g, S, E, wave);
.Lp1_poll_c0:
	global_load_dword v237, v236, s[68:69] sc1
	s_waitcnt vmcnt(0)
	v_readfirstlane_b32 s101, v237
	s_cmpk_ge_u32 s101, 0x100
	s_cbranch_scc1 .Lp1_got_c0
	s_add_i32 s100, s100, 1
	s_cmp_lt_u32 s100, 0x10000
	s_cbranch_scc0 .Lp1_got_c0
	s_sleep 6
	s_branch .Lp1_poll_c0

; __global__ void __launch_bounds__(NWAVES * 64, 2) fwd_kernel(Args a) {
;     ...
;     if (IN(3)) for (int rep = 0; rep < NREP(3); ++rep) {
;         pg8::Gemm g{Y, WT2, NTOK, DM, GW}; pg8::StaticOrder S; S.init(NTOK, DM, G, bx);
;         pg8::EpiRes1 E{HN0, IRS0, H1B, HSS1};
;         pg8::gemm_phase<pg8::EpiRes1, pg8::StaticOrder, GEMM_ALIGN, GEMM_SP2>(lds, g, S, E, wave);
.Lp3_poll:
	global_load_dword v237, v236, s[98:99] sc1
	s_waitcnt vmcnt(0)
	v_readfirstlane_b32 s101, v237
	s_cmpk_ge_u32 s101, 0x100
	s_cbranch_scc1 .Lp3_meet
	s_add_i32 s100, s100, 1
	s_cmp_lt_u32 s100, 0x10000
	s_cbranch_scc0 .Lp3_meet
	s_sleep 6
	s_branch .Lp3_poll

; __global__ void __launch_bounds__(NWAVES * 64, 2) fwd_kernel(Args a) {
;     ...
;     if (IN(4)) for (int rep = 0; rep < NREP(4); ++rep) {
;         pg8::Gemm g{H1B, WT3, NTOK, 4 * DM, DM}; pg8::StaticOrder S; S.init(NTOK, 4 * DM, G, bx);
;         pg8::EpiSbIn E{Qb, (size_t)(WS_K - WS_Q) / 2, HSS1};
;         pg8::gemm_phase<pg8::EpiSbIn, pg8::StaticOrder, GEMM_ALIGN, GEMM_SP2>(lds, g, S, E, wave);
.Lp4_poll:
	global_load_dword v237, v236, s[98:99] sc1
	s_waitcnt vmcnt(0)
	v_readfirstlane_b32 s101, v237
	s_cmpk_ge_u32 s101, 0x40
	s_cbranch_scc1 .Lp4_meet
	s_add_i32 s100, s100, 1
	s_cmp_lt_u32 s100, 0x10000
	s_cbranch_scc0 .Lp4_meet
	s_sleep 6
	s_branch .Lp4_poll

; __global__ void __launch_bounds__(NWAVES * 64, 2) fwd_kernel(Args a) {
;     ...
;     if (IN(6)) for (int rep = 0; rep < NREP(6); ++rep) {
;         pg8::Gemm g{OG, WT4, NTOK, DM, DM}; pg8::StaticOrder S; S.init(NTOK, DM, G, bx);
;         pg8::EpiFinal E{H1B, final_g, a.out, HSS2, CNT, G == 256};
;         pg8::gemm_phase<pg8::EpiFinal, pg8::StaticOrder, GEMM_ALIGN, GEMM_SP2>(lds, g, S, E, wave);
.Lp6_poll:
	global_load_dword v237, v236, s[98:99] sc1
	s_waitcnt vmcnt(0)
	v_readfirstlane_b32 s101, v237
	s_cmpk_ge_u32 s101, 0x80
	s_cbranch_scc1 .Lp6_meet
	s_add_i32 s100, s100, 1
	s_cmp_lt_u32 s100, 0x10000
	s_cbranch_scc0 .Lp6_meet
	s_sleep 6
	s_branch .Lp6_poll
